# P9 K-loop: LDS-DMA staging rebalanced 4/4 per super-phase (As[b][0] stage moved to next SP1 segment, vmcnt 6/8)
# baseline (speedup 1.0000x reference)
; #define PG8_STAGE(bufoff, gbase, voff) do { _Pragma("unroll") for (int _i = 0; _i < 2; ++_i) \
;         __builtin_amdgcn_global_load_lds((const unsigned*)((const char*)(gbase) + (voff)[_i]), (PG8_LAS unsigned*)(lds + (bufoff) + ldsw + _i * 8192), 16, 0, 0); } while (0)
; #define PG8_LDA(dst, b, h) do { _Pragma("unroll") for (int m = 0; m < 4; ++m) _Pragma("unroll") for (int k = 0; k < 2; ++k) dst[m][k] = *(const PG8_LAS bf16x8*)(lds + PG8_SA(b, h) + aoff + m * 2048 + k * 1024); } while (0)
; #define PG8_LDB(dst, b, h) do { _Pragma("unroll") for (int n = 0; n < 2; ++n) _Pragma("unroll") for (int k = 0; k < 2; ++k) dst[n][k] = *(const PG8_LAS bf16x8*)(lds + PG8_SB(b, h) + boff + n * 2048 + k * 1024); } while (0)
; #define PG8_MMA(ai, bj, At, Bt) do { __builtin_amdgcn_s_setprio(1); _Pragma("unroll") for (int m = 0; m < 4; ++m) _Pragma("unroll") for (int n = 0; n < 2; ++n) _Pragma("unroll") for (int k = 0; k < 2; ++k) \
;         acc[ai][bj][m][n] = __builtin_amdgcn_mfma_f32_16x16x32_bf16(Bt[n][k], At[m][k], acc[ai][bj][m][n], 0, 0, 0); __builtin_amdgcn_s_setprio(0); } while (0)
; #define PG8_WAIT_V(n) asm volatile("s_waitcnt vmcnt(" #n ")" ::: "memory")
; #define PG8_WAIT_L(n) asm volatile("s_waitcnt lgkmcnt(" #n ")" ::: "memory")
; #define PG8_BAR __builtin_amdgcn_s_barrier()
; #define PG8_SCHED __builtin_amdgcn_sched_barrier(0)
; template <class Epi, class Sched, bool ALIGN_EPI = false, bool SP2 = false>
; __device__ __forceinline__ void gemm_phase(PG8_LAS unsigned char* lds, const Gemm g, const Sched& S, const Epi& E) {
;     ...
;             PG8_LDB(B0, 0, 0); PG8_LDB(B1, 0, 1); PG8_SCHED; PG8_LDA(At, 0, 0); PG8_STAGE(PG8_SA(1, 1), a1 + hstep, voffA);
;             PG8_WAIT_V(8); PG8_WAIT_L(0); PG8_BAR; PG8_MMA(0, 0, At, B0); PG8_MMA(0, 1, At, B1); PG8_BAR; PG8_SCHED;
;             PG8_LDA(At, 0, 1); PG8_STAGE(PG8_SB(0, 0), b2, voffB); PG8_STAGE(PG8_SB(0, 1), b2 + hstep, voffB); PG8_STAGE(PG8_SA(0, 0), a2, voffA);
;             PG8_WAIT_V(8); PG8_WAIT_L(0); PG8_BAR; PG8_MMA(1, 0, At, B0); PG8_MMA(1, 1, At, B1); PG8_BAR; PG8_SCHED;
.LBB0_1164:
	s_add_u32 s16, s14, 0xffd50000
	s_addc_u32 s17, s15, -1
	v_lshl_add_u64 v[188:189], s[16:17], 0, v[128:129]
	s_mov_b32 m0, s29
	s_nop 0
	global_load_lds_dwordx4 v[188:189], off
	v_lshl_add_u64 v[188:189], s[16:17], 0, v[130:131]
	s_mov_b32 m0, s30
	s_nop 0
	global_load_lds_dwordx4 v[188:189], off
	s_add_u32 s16, s16, 0x80
	s_addc_u32 s17, s17, 0
	ds_read_b128 v[140:143], v193
	ds_read_b128 v[144:147], v193 offset:1024
	ds_read_b128 v[148:151], v193 offset:2048
	ds_read_b128 v[152:155], v193 offset:3072
	ds_read_b128 v[156:159], v194
	ds_read_b128 v[160:163], v194 offset:1024
	ds_read_b128 v[164:167], v194 offset:2048
	ds_read_b128 v[168:171], v194 offset:3072
	s_cmpk_eq_i32 s41, 0xa8
	s_cselect_b32 s21, s5, s17
	s_cselect_b32 s20, s4, s16
	s_cselect_b32 s17, s13, s40
	s_cselect_b32 s16, s12, s39
	v_lshl_add_u64 v[188:189], s[14:15], 0, v[132:133]
	s_add_i32 m0, s24, 0xc000
	ds_read_b128 v[172:175], v195
	ds_read_b128 v[176:179], v195 offset:1024
	ds_read_b128 v[180:183], v195 offset:2048
	ds_read_b128 v[184:187], v195 offset:3072
	ds_read_b128 v[196:199], v195 offset:4096
	ds_read_b128 v[200:203], v195 offset:5120
	ds_read_b128 v[204:207], v195 offset:6144
	ds_read_b128 v[208:211], v195 offset:7168
	global_load_lds_dwordx4 v[188:189], off
	v_lshl_add_u64 v[188:189], s[14:15], 0, v[134:135]
	s_add_i32 m0, s24, 0xe000
	s_nop 0
	global_load_lds_dwordx4 v[188:189], off
	s_waitcnt vmcnt(8)
	s_waitcnt lgkmcnt(0)
	s_barrier
	s_setprio 1
	s_waitcnt lgkmcnt(0)
	v_mfma_f32_16x16x32_bf16 v[124:127], v[140:143], v[172:175], v[124:127]
	v_mfma_f32_16x16x32_bf16 v[120:123], v[148:151], v[172:175], v[120:123]
	v_mfma_f32_16x16x32_bf16 v[112:115], v[140:143], v[180:183], v[112:115]
	v_mfma_f32_16x16x32_bf16 v[104:107], v[148:151], v[180:183], v[104:107]
	v_mfma_f32_16x16x32_bf16 v[96:99], v[140:143], v[196:199], v[96:99]
	v_mfma_f32_16x16x32_bf16 v[88:91], v[148:151], v[196:199], v[88:91]
	v_mfma_f32_16x16x32_bf16 v[80:83], v[140:143], v[204:207], v[80:83]
	v_mfma_f32_16x16x32_bf16 v[72:75], v[148:151], v[204:207], v[72:75]
	v_mfma_f32_16x16x32_bf16 v[124:127], v[144:147], v[176:179], v[124:127]
	v_mfma_f32_16x16x32_bf16 v[120:123], v[152:155], v[176:179], v[120:123]
	v_mfma_f32_16x16x32_bf16 v[112:115], v[144:147], v[184:187], v[112:115]
	v_mfma_f32_16x16x32_bf16 v[104:107], v[152:155], v[184:187], v[104:107]
	v_mfma_f32_16x16x32_bf16 v[96:99], v[144:147], v[200:203], v[96:99]
	v_mfma_f32_16x16x32_bf16 v[88:91], v[152:155], v[200:203], v[88:91]
	v_mfma_f32_16x16x32_bf16 v[80:83], v[144:147], v[208:211], v[80:83]
	v_mfma_f32_16x16x32_bf16 v[72:75], v[152:155], v[208:211], v[72:75]
	s_setprio 0
	s_setprio 1
	v_mfma_f32_16x16x32_bf16 v[116:119], v[156:159], v[172:175], v[116:119]
	v_mfma_f32_16x16x32_bf16 v[108:111], v[164:167], v[172:175], v[108:111]
	v_mfma_f32_16x16x32_bf16 v[100:103], v[156:159], v[180:183], v[100:103]
	v_mfma_f32_16x16x32_bf16 v[92:95], v[164:167], v[180:183], v[92:95]
	v_mfma_f32_16x16x32_bf16 v[84:87], v[156:159], v[196:199], v[84:87]
	v_mfma_f32_16x16x32_bf16 v[76:79], v[164:167], v[196:199], v[76:79]
	v_mfma_f32_16x16x32_bf16 v[68:71], v[156:159], v[204:207], v[68:71]
	v_mfma_f32_16x16x32_bf16 v[64:67], v[164:167], v[204:207], v[64:67]
	v_mfma_f32_16x16x32_bf16 v[116:119], v[160:163], v[176:179], v[116:119]
	v_mfma_f32_16x16x32_bf16 v[108:111], v[168:171], v[176:179], v[108:111]
	v_mfma_f32_16x16x32_bf16 v[100:103], v[160:163], v[184:187], v[100:103]
	v_mfma_f32_16x16x32_bf16 v[92:95], v[168:171], v[184:187], v[92:95]
	v_mfma_f32_16x16x32_bf16 v[84:87], v[160:163], v[200:203], v[84:87]
	v_mfma_f32_16x16x32_bf16 v[76:79], v[168:171], v[200:203], v[76:79]
	v_mfma_f32_16x16x32_bf16 v[68:71], v[160:163], v[208:211], v[68:71]
	v_mfma_f32_16x16x32_bf16 v[64:67], v[168:171], v[208:211], v[64:67]
	s_setprio 0
	s_barrier
	s_add_i32 s42, s33, s23
	v_lshl_add_u64 v[188:189], s[16:17], 0, v[128:129]
	s_mov_b32 m0, s42
	ds_read_b128 v[172:175], v195 offset:16384
	ds_read_b128 v[176:179], v195 offset:17408
	ds_read_b128 v[180:183], v195 offset:18432
	ds_read_b128 v[184:187], v195 offset:19456
	ds_read_b128 v[196:199], v195 offset:20480
	ds_read_b128 v[200:203], v195 offset:21504
	ds_read_b128 v[204:207], v195 offset:22528
	ds_read_b128 v[208:211], v195 offset:23552
	global_load_lds_dwordx4 v[188:189], off
	s_add_i32 m0, s42, 0x2000
	s_add_u32 s42, s16, 0x2b0000
	v_lshl_add_u64 v[212:213], s[16:17], 0, v[130:131]
	s_addc_u32 s43, s17, 0
	s_add_i32 s44, s34, s23
	global_load_lds_dwordx4 v[212:213], off
	v_lshl_add_u64 v[214:215], s[42:43], 0, v[128:129]
	s_mov_b32 m0, s44
	v_lshl_add_u64 v[216:217], s[20:21], 0, v[130:131]
	global_load_lds_dwordx4 v[214:215], off
	v_lshl_add_u64 v[214:215], s[42:43], 0, v[130:131]
	s_add_i32 m0, s44, 0x2000
	s_nop 0
	global_load_lds_dwordx4 v[214:215], off
	v_lshl_add_u64 v[214:215], s[20:21], 0, v[128:129]
	s_waitcnt vmcnt(6)
	s_waitcnt lgkmcnt(0)
	s_barrier
; #define PG8_STAGE(bufoff, gbase, voff) do { _Pragma("unroll") for (int _i = 0; _i < 2; ++_i) \
;         __builtin_amdgcn_global_load_lds((const unsigned*)((const char*)(gbase) + (voff)[_i]), (PG8_LAS unsigned*)(lds + (bufoff) + ldsw + _i * 8192), 16, 0, 0); } while (0)
; #define PG8_LDA(dst, b, h) do { _Pragma("unroll") for (int m = 0; m < 4; ++m) _Pragma("unroll") for (int k = 0; k < 2; ++k) dst[m][k] = *(const PG8_LAS bf16x8*)(lds + PG8_SA(b, h) + aoff + m * 2048 + k * 1024); } while (0)
; #define PG8_LDB(dst, b, h) do { _Pragma("unroll") for (int n = 0; n < 2; ++n) _Pragma("unroll") for (int k = 0; k < 2; ++k) dst[n][k] = *(const PG8_LAS bf16x8*)(lds + PG8_SB(b, h) + boff + n * 2048 + k * 1024); } while (0)
; #define PG8_MMA(ai, bj, At, Bt) do { __builtin_amdgcn_s_setprio(1); _Pragma("unroll") for (int m = 0; m < 4; ++m) _Pragma("unroll") for (int n = 0; n < 2; ++n) _Pragma("unroll") for (int k = 0; k < 2; ++k) \
;         acc[ai][bj][m][n] = __builtin_amdgcn_mfma_f32_16x16x32_bf16(Bt[n][k], At[m][k], acc[ai][bj][m][n], 0, 0, 0); __builtin_amdgcn_s_setprio(0); } while (0)
; #define PG8_WAIT_V(n) asm volatile("s_waitcnt vmcnt(" #n ")" ::: "memory")
; #define PG8_WAIT_L(n) asm volatile("s_waitcnt lgkmcnt(" #n ")" ::: "memory")
; #define PG8_BAR __builtin_amdgcn_s_barrier()
; #define PG8_SCHED __builtin_amdgcn_sched_barrier(0)
; template <class Epi, class Sched, bool ALIGN_EPI = false, bool SP2 = false>
; __device__ __forceinline__ void gemm_phase(PG8_LAS unsigned char* lds, const Gemm g, const Sched& S, const Epi& E) {
;     ...
;             PG8_WAIT_V(8); PG8_WAIT_L(0); PG8_BAR; PG8_MMA(1, 0, At, B0); PG8_MMA(1, 1, At, B1); PG8_BAR; PG8_SCHED;
;             PG8_LDB(B0, 1, 0); PG8_LDB(B1, 1, 1); PG8_SCHED; PG8_LDA(At, 1, 0); PG8_STAGE(PG8_SA(0, 1), a2 + hstep, voffA);
	s_setprio 1
	s_waitcnt lgkmcnt(0)
	v_mfma_f32_16x16x32_bf16 v[60:63], v[140:143], v[172:175], v[60:63]
	v_mfma_f32_16x16x32_bf16 v[56:59], v[148:151], v[172:175], v[56:59]
	v_mfma_f32_16x16x32_bf16 v[48:51], v[140:143], v[180:183], v[48:51]
	v_mfma_f32_16x16x32_bf16 v[40:43], v[148:151], v[180:183], v[40:43]
	v_mfma_f32_16x16x32_bf16 v[32:35], v[140:143], v[196:199], v[32:35]
	v_mfma_f32_16x16x32_bf16 v[24:27], v[148:151], v[196:199], v[24:27]
	v_mfma_f32_16x16x32_bf16 v[16:19], v[140:143], v[204:207], v[16:19]
	v_mfma_f32_16x16x32_bf16 v[8:11], v[148:151], v[204:207], v[8:11]
	v_mfma_f32_16x16x32_bf16 v[60:63], v[144:147], v[176:179], v[60:63]
	v_mfma_f32_16x16x32_bf16 v[56:59], v[152:155], v[176:179], v[56:59]
	v_mfma_f32_16x16x32_bf16 v[48:51], v[144:147], v[184:187], v[48:51]
	v_mfma_f32_16x16x32_bf16 v[40:43], v[152:155], v[184:187], v[40:43]
	v_mfma_f32_16x16x32_bf16 v[32:35], v[144:147], v[200:203], v[32:35]
	v_mfma_f32_16x16x32_bf16 v[24:27], v[152:155], v[200:203], v[24:27]
	v_mfma_f32_16x16x32_bf16 v[16:19], v[144:147], v[208:211], v[16:19]
	v_mfma_f32_16x16x32_bf16 v[8:11], v[152:155], v[208:211], v[8:11]
	s_setprio 0
	s_setprio 1
	v_mfma_f32_16x16x32_bf16 v[52:55], v[156:159], v[172:175], v[52:55]
	v_mfma_f32_16x16x32_bf16 v[44:47], v[164:167], v[172:175], v[44:47]
	v_mfma_f32_16x16x32_bf16 v[36:39], v[156:159], v[180:183], v[36:39]
	v_mfma_f32_16x16x32_bf16 v[28:31], v[164:167], v[180:183], v[28:31]
	v_mfma_f32_16x16x32_bf16 v[20:23], v[156:159], v[196:199], v[20:23]
	v_mfma_f32_16x16x32_bf16 v[12:15], v[164:167], v[196:199], v[12:15]
	v_mfma_f32_16x16x32_bf16 v[4:7], v[156:159], v[204:207], v[4:7]
	v_mfma_f32_16x16x32_bf16 v[0:3], v[164:167], v[204:207], v[0:3]
	v_mfma_f32_16x16x32_bf16 v[52:55], v[160:163], v[176:179], v[52:55]
	v_mfma_f32_16x16x32_bf16 v[44:47], v[168:171], v[176:179], v[44:47]
	v_mfma_f32_16x16x32_bf16 v[36:39], v[160:163], v[184:187], v[36:39]
	v_mfma_f32_16x16x32_bf16 v[28:31], v[168:171], v[184:187], v[28:31]
	v_mfma_f32_16x16x32_bf16 v[20:23], v[160:163], v[200:203], v[20:23]
	v_mfma_f32_16x16x32_bf16 v[12:15], v[168:171], v[200:203], v[12:15]
	v_mfma_f32_16x16x32_bf16 v[4:7], v[160:163], v[208:211], v[4:7]
	v_mfma_f32_16x16x32_bf16 v[0:3], v[168:171], v[208:211], v[0:3]
	s_setprio 0
	s_barrier
	s_mov_b32 m0, s24
	s_nop 0
	global_load_lds_dwordx4 v[214:215], off
	s_mov_b32 m0, s25
	s_nop 0
	global_load_lds_dwordx4 v[216:217], off
	s_add_i32 s42, 0, 0x18000
	s_add_i32 s43, 0, 0x1c000
	v_add_u32_e32 v152, s42, v191
	v_add_u32_e32 v168, s43, v191
	ds_read_b128 v[140:143], v152
	ds_read_b128 v[144:147], v152 offset:1024
	ds_read_b128 v[148:151], v152 offset:2048
	ds_read_b128 v[152:155], v152 offset:3072
	ds_read_b128 v[156:159], v168
	ds_read_b128 v[160:163], v168 offset:1024
	ds_read_b128 v[164:167], v168 offset:2048
	ds_read_b128 v[168:171], v168 offset:3072
	s_add_u32 s20, s20, 0x2b0000
	s_addc_u32 s21, s21, 0
	s_mov_b32 m0, s26
	v_lshl_add_u64 v[218:219], s[20:21], 0, v[128:129]
	ds_read_b128 v[172:175], v195 offset:32768
	ds_read_b128 v[176:179], v195 offset:33792
	ds_read_b128 v[180:183], v195 offset:34816
	ds_read_b128 v[184:187], v195 offset:35840
	ds_read_b128 v[196:199], v195 offset:36864
	ds_read_b128 v[200:203], v195 offset:37888
	ds_read_b128 v[204:207], v195 offset:38912
	ds_read_b128 v[208:211], v195 offset:39936
	global_load_lds_dwordx4 v[218:219], off
	v_lshl_add_u64 v[218:219], s[20:21], 0, v[130:131]
	s_mov_b32 m0, s27
	s_nop 0
	global_load_lds_dwordx4 v[218:219], off
	s_waitcnt vmcnt(8)
	s_waitcnt lgkmcnt(0)
	s_barrier
; #define PG8_STAGE(bufoff, gbase, voff) do { _Pragma("unroll") for (int _i = 0; _i < 2; ++_i) \
;         __builtin_amdgcn_global_load_lds((const unsigned*)((const char*)(gbase) + (voff)[_i]), (PG8_LAS unsigned*)(lds + (bufoff) + ldsw + _i * 8192), 16, 0, 0); } while (0)
; #define PG8_LDA(dst, b, h) do { _Pragma("unroll") for (int m = 0; m < 4; ++m) _Pragma("unroll") for (int k = 0; k < 2; ++k) dst[m][k] = *(const PG8_LAS bf16x8*)(lds + PG8_SA(b, h) + aoff + m * 2048 + k * 1024); } while (0)
; #define PG8_MMA(ai, bj, At, Bt) do { __builtin_amdgcn_s_setprio(1); _Pragma("unroll") for (int m = 0; m < 4; ++m) _Pragma("unroll") for (int n = 0; n < 2; ++n) _Pragma("unroll") for (int k = 0; k < 2; ++k) \
;         acc[ai][bj][m][n] = __builtin_amdgcn_mfma_f32_16x16x32_bf16(Bt[n][k], At[m][k], acc[ai][bj][m][n], 0, 0, 0); __builtin_amdgcn_s_setprio(0); } while (0)
; #define PG8_WAIT_V(n) asm volatile("s_waitcnt vmcnt(" #n ")" ::: "memory")
; #define PG8_WAIT_L(n) asm volatile("s_waitcnt lgkmcnt(" #n ")" ::: "memory")
; #define PG8_BAR __builtin_amdgcn_s_barrier()
; #define PG8_SCHED __builtin_amdgcn_sched_barrier(0)
; template <class Epi, class Sched, bool ALIGN_EPI = false, bool SP2 = false>
; __device__ __forceinline__ void gemm_phase(PG8_LAS unsigned char* lds, const Gemm g, const Sched& S, const Epi& E) {
;     ...
;         for (int t = 0; t < nt; t += 2) {
;             const bool last = (t == nt - 2);
;             const char* a1 = cA + (size_t)(t + 1) * kstep;
;             const char* a2 = last ? nA : cA + (size_t)(t + 2) * kstep; const char* b2 = last ? nB : cB + (size_t)(t + 2) * kstep;
;     ...
;             PG8_WAIT_V(8); PG8_WAIT_L(0); PG8_BAR; PG8_MMA(0, 0, At, B0); PG8_MMA(0, 1, At, B1); PG8_BAR; PG8_SCHED;
;             PG8_LDA(At, 1, 1); PG8_STAGE(PG8_SB(1, 0), b3, voffB); PG8_STAGE(PG8_SB(1, 1), b3 + hstep, voffB); PG8_STAGE(PG8_SA(1, 0), a3, voffA);
;             PG8_WAIT_V(8); PG8_WAIT_L(0); PG8_BAR; PG8_MMA(1, 0, At, B0); PG8_MMA(1, 1, At, B1); PG8_BAR; PG8_SCHED;
	s_setprio 1
	s_waitcnt lgkmcnt(0)
	v_mfma_f32_16x16x32_bf16 v[124:127], v[140:143], v[172:175], v[124:127]
	v_mfma_f32_16x16x32_bf16 v[120:123], v[148:151], v[172:175], v[120:123]
	v_mfma_f32_16x16x32_bf16 v[112:115], v[140:143], v[180:183], v[112:115]
	v_mfma_f32_16x16x32_bf16 v[104:107], v[148:151], v[180:183], v[104:107]
	v_mfma_f32_16x16x32_bf16 v[96:99], v[140:143], v[196:199], v[96:99]
	v_mfma_f32_16x16x32_bf16 v[88:91], v[148:151], v[196:199], v[88:91]
	v_mfma_f32_16x16x32_bf16 v[80:83], v[140:143], v[204:207], v[80:83]
	v_mfma_f32_16x16x32_bf16 v[72:75], v[148:151], v[204:207], v[72:75]
	v_mfma_f32_16x16x32_bf16 v[124:127], v[144:147], v[176:179], v[124:127]
	v_mfma_f32_16x16x32_bf16 v[120:123], v[152:155], v[176:179], v[120:123]
	v_mfma_f32_16x16x32_bf16 v[112:115], v[144:147], v[184:187], v[112:115]
	v_mfma_f32_16x16x32_bf16 v[104:107], v[152:155], v[184:187], v[104:107]
	v_mfma_f32_16x16x32_bf16 v[96:99], v[144:147], v[200:203], v[96:99]
	v_mfma_f32_16x16x32_bf16 v[88:91], v[152:155], v[200:203], v[88:91]
	v_mfma_f32_16x16x32_bf16 v[80:83], v[144:147], v[208:211], v[80:83]
	v_mfma_f32_16x16x32_bf16 v[72:75], v[152:155], v[208:211], v[72:75]
	s_setprio 0
	s_setprio 1
	v_mfma_f32_16x16x32_bf16 v[116:119], v[156:159], v[172:175], v[116:119]
	v_mfma_f32_16x16x32_bf16 v[108:111], v[164:167], v[172:175], v[108:111]
	v_mfma_f32_16x16x32_bf16 v[100:103], v[156:159], v[180:183], v[100:103]
	v_mfma_f32_16x16x32_bf16 v[92:95], v[164:167], v[180:183], v[92:95]
	v_mfma_f32_16x16x32_bf16 v[84:87], v[156:159], v[196:199], v[84:87]
	v_mfma_f32_16x16x32_bf16 v[76:79], v[164:167], v[196:199], v[76:79]
	v_mfma_f32_16x16x32_bf16 v[68:71], v[156:159], v[204:207], v[68:71]
	v_mfma_f32_16x16x32_bf16 v[64:67], v[164:167], v[204:207], v[64:67]
	v_mfma_f32_16x16x32_bf16 v[116:119], v[160:163], v[176:179], v[116:119]
	v_mfma_f32_16x16x32_bf16 v[108:111], v[168:171], v[176:179], v[108:111]
	v_mfma_f32_16x16x32_bf16 v[100:103], v[160:163], v[184:187], v[100:103]
	v_mfma_f32_16x16x32_bf16 v[92:95], v[168:171], v[184:187], v[92:95]
	v_mfma_f32_16x16x32_bf16 v[84:87], v[160:163], v[200:203], v[84:87]
	v_mfma_f32_16x16x32_bf16 v[76:79], v[168:171], v[200:203], v[76:79]
	v_mfma_f32_16x16x32_bf16 v[68:71], v[160:163], v[208:211], v[68:71]
	v_mfma_f32_16x16x32_bf16 v[64:67], v[168:171], v[208:211], v[64:67]
	s_setprio 0
	s_barrier
	s_add_i32 s20, s42, s23
	v_lshl_add_u64 v[188:189], v[188:189], 0, s[8:9]
	s_mov_b32 m0, s20
	ds_read_b128 v[172:175], v195 offset:49152
	ds_read_b128 v[176:179], v195 offset:50176
	ds_read_b128 v[180:183], v195 offset:51200
	ds_read_b128 v[184:187], v195 offset:52224
	ds_read_b128 v[196:199], v195 offset:53248
	ds_read_b128 v[200:203], v195 offset:54272
	ds_read_b128 v[204:207], v195 offset:55296
	ds_read_b128 v[208:211], v195 offset:56320
	global_load_lds_dwordx4 v[188:189], off
	s_add_i32 m0, s20, 0x2000
	s_add_u32 s16, s16, 0x2b0080
	v_lshl_add_u64 v[188:189], v[212:213], 0, s[8:9]
	s_addc_u32 s17, s17, 0
	s_add_i32 s20, s43, s23
	global_load_lds_dwordx4 v[188:189], off
	v_lshl_add_u64 v[188:189], s[16:17], 0, v[128:129]
	s_mov_b32 m0, s20
	s_nop 0
	global_load_lds_dwordx4 v[188:189], off
	v_lshl_add_u64 v[188:189], s[16:17], 0, v[130:131]
	s_add_i32 m0, s20, 0x2000
	s_nop 0
	global_load_lds_dwordx4 v[188:189], off
	s_waitcnt vmcnt(6)
	s_waitcnt lgkmcnt(0)
	s_barrier
	s_setprio 1
	s_waitcnt lgkmcnt(0)
	v_mfma_f32_16x16x32_bf16 v[60:63], v[140:143], v[172:175], v[60:63]
	v_mfma_f32_16x16x32_bf16 v[56:59], v[148:151], v[172:175], v[56:59]
	v_mfma_f32_16x16x32_bf16 v[48:51], v[140:143], v[180:183], v[48:51]
	v_mfma_f32_16x16x32_bf16 v[40:43], v[148:151], v[180:183], v[40:43]
	v_mfma_f32_16x16x32_bf16 v[32:35], v[140:143], v[196:199], v[32:35]
	v_mfma_f32_16x16x32_bf16 v[24:27], v[148:151], v[196:199], v[24:27]
	v_mfma_f32_16x16x32_bf16 v[16:19], v[140:143], v[204:207], v[16:19]
	v_mfma_f32_16x16x32_bf16 v[8:11], v[148:151], v[204:207], v[8:11]
	v_mfma_f32_16x16x32_bf16 v[60:63], v[144:147], v[176:179], v[60:63]
	v_mfma_f32_16x16x32_bf16 v[56:59], v[152:155], v[176:179], v[56:59]
	v_mfma_f32_16x16x32_bf16 v[48:51], v[144:147], v[184:187], v[48:51]
	v_mfma_f32_16x16x32_bf16 v[40:43], v[152:155], v[184:187], v[40:43]
	v_mfma_f32_16x16x32_bf16 v[32:35], v[144:147], v[200:203], v[32:35]
	v_mfma_f32_16x16x32_bf16 v[24:27], v[152:155], v[200:203], v[24:27]
	v_mfma_f32_16x16x32_bf16 v[16:19], v[144:147], v[208:211], v[16:19]
	v_mfma_f32_16x16x32_bf16 v[8:11], v[152:155], v[208:211], v[8:11]
	s_setprio 0
	s_setprio 1
	v_mfma_f32_16x16x32_bf16 v[52:55], v[156:159], v[172:175], v[52:55]
	v_mfma_f32_16x16x32_bf16 v[44:47], v[164:167], v[172:175], v[44:47]
	v_mfma_f32_16x16x32_bf16 v[36:39], v[156:159], v[180:183], v[36:39]
	v_mfma_f32_16x16x32_bf16 v[28:31], v[164:167], v[180:183], v[28:31]
	v_mfma_f32_16x16x32_bf16 v[20:23], v[156:159], v[196:199], v[20:23]
	v_mfma_f32_16x16x32_bf16 v[12:15], v[164:167], v[196:199], v[12:15]
	v_mfma_f32_16x16x32_bf16 v[4:7], v[156:159], v[204:207], v[4:7]
	v_mfma_f32_16x16x32_bf16 v[0:3], v[164:167], v[204:207], v[0:3]
	v_mfma_f32_16x16x32_bf16 v[52:55], v[160:163], v[176:179], v[52:55]
	v_mfma_f32_16x16x32_bf16 v[44:47], v[168:171], v[176:179], v[44:47]
	v_mfma_f32_16x16x32_bf16 v[36:39], v[160:163], v[184:187], v[36:39]
	v_mfma_f32_16x16x32_bf16 v[28:31], v[168:171], v[184:187], v[28:31]
	v_mfma_f32_16x16x32_bf16 v[20:23], v[160:163], v[200:203], v[20:23]
	v_mfma_f32_16x16x32_bf16 v[12:15], v[168:171], v[200:203], v[12:15]
	v_mfma_f32_16x16x32_bf16 v[4:7], v[160:163], v[208:211], v[4:7]
	v_mfma_f32_16x16x32_bf16 v[0:3], v[168:171], v[208:211], v[0:3]
	s_setprio 0
	s_barrier
	s_add_i32 s41, s41, 2
	s_add_u32 s14, s14, 0x100
	s_addc_u32 s15, s15, 0
	s_add_u32 s39, s39, 0x100
	s_addc_u32 s40, s40, 0
	s_cmpk_gt_u32 s41, 0xa9
	s_cbranch_scc0 .LBB0_1164
	s_and_b64 vcc, exec, s[10:11]
	s_cbranch_vccz .LBB0_1167
	s_barrier
